# GEMM k-loops: saddr global loads in MFMA gaps 1-8 + LDS writes in gaps 9-16; T1 (MLA) next-tile loads moved into QK MFMA gaps (saddr); T0 loads saddr
# speedup vs baseline: 1.0310x; 1.0147x over previous
; #define GL(...) GLOAD(__VA_ARGS__)
; #define SS(...) SSTORE(__VA_ARGS__)
; template <bool TRANS>
; DI void gemm_kloop(const u16* __restrict__ A, int lda, const u16* __restrict__ W, int ldw, int K, f32x16 (&acc)[2][2], char* lds) {
;     ...
;   GL(SET0, 0);
;   SS(SET0, 0);
;   GL(SET1, 64);
;   __syncthreads();
;   for (int kt = 0; kt < KT; kt += 2) {
;     const bool m2 = kt + 2 < KT;
;     if (m2) { GL(SET0, (kt + 2) * 64); }
;     COMPUTE(0);
;     SS(SET1, 1);
;     __syncthreads();
;     if (m2) { GL(SET1, (kt + 3) * 64); }
;     COMPUTE(1);
;     if (m2) { SS(SET0, 0); }
;     __syncthreads();
;   }
.LBB0_160:
	s_cmp_lt_u32 s52, s44
	s_cselect_b64 s[98:99], -1, 0
	s_cmp_ge_u32 s52, s44
	s_cselect_b64 s[30:31], -1, 0
	s_and_b64 vcc, exec, s[30:31]
	s_cbranch_vccnz .Lggc_last
	v_add_u32_e32 v169, v165, v163
	ds_read_b128 v[196:199], v169 offset:16384
	v_add_u32_e32 v170, v164, v163
	ds_read_b128 v[200:203], v170
	ds_read_b128 v[204:207], v170 offset:4096
	ds_read_b128 v[208:211], v169 offset:20480
	v_add_u32_e32 v171, v164, v166
	v_add_u32_e32 v172, v165, v166
	s_waitcnt lgkmcnt(0)
	v_mfma_f32_32x32x16_bf16 v[34:49], v[208:211], v[200:203], v[34:49]
	global_load_dwordx4 v[66:69], v0, s[6:7] offset:256
	v_mfma_f32_32x32x16_bf16 v[50:65], v[196:199], v[200:203], v[50:65]
	global_load_dwordx4 v[70:73], v0, s[16:17] offset:256
	v_mfma_f32_32x32x16_bf16 v[18:33], v[196:199], v[204:207], v[18:33]
	global_load_dwordx4 v[74:77], v0, s[22:23] offset:256
	ds_read_b128 v[196:199], v171
	ds_read_b128 v[200:203], v171 offset:4096
	ds_read_b128 v[212:215], v172 offset:16384
	ds_read_b128 v[226:229], v172 offset:20480
	v_mfma_f32_32x32x16_bf16 v[2:17], v[208:211], v[204:207], v[2:17]
	global_load_dwordx4 v[78:81], v0, s[18:19] offset:256
	s_waitcnt lgkmcnt(1)
	v_mfma_f32_32x32x16_bf16 v[50:65], v[212:215], v[196:199], v[50:65]
	global_load_dwordx4 v[82:85], v0, s[24:25] offset:256
	v_add_u32_e32 v173, v164, v167
	v_add_u32_e32 v190, v165, v167
	s_waitcnt lgkmcnt(0)
	v_mfma_f32_32x32x16_bf16 v[34:49], v[226:229], v[196:199], v[34:49]
	global_load_dwordx4 v[86:89], v0, s[28:29] offset:256
	ds_read_b128 v[196:199], v173
	ds_read_b128 v[204:207], v173 offset:4096
	v_mfma_f32_32x32x16_bf16 v[18:33], v[212:215], v[200:203], v[18:33]
	global_load_dwordx4 v[90:93], v0, s[50:51] offset:-128
	ds_read_b128 v[208:211], v190 offset:16384
	ds_read_b128 v[212:215], v190 offset:20480
	v_mfma_f32_32x32x16_bf16 v[2:17], v[226:229], v[200:203], v[2:17]
	global_load_dwordx4 v[94:97], v0, s[36:37] offset:256
	s_waitcnt lgkmcnt(1)
	v_mfma_f32_32x32x16_bf16 v[50:65], v[208:211], v[196:199], v[50:65]
	s_waitcnt vmcnt(8)
	ds_write_b128 v162, v[98:101] offset:32768
	v_add_u32_e32 v194, v164, v168
	s_waitcnt lgkmcnt(1)
	v_mfma_f32_32x32x16_bf16 v[34:49], v[212:215], v[196:199], v[34:49]
	ds_write_b128 v162, v[102:105] offset:36864
	v_add_u32_e32 v196, v165, v168
	v_mfma_f32_32x32x16_bf16 v[18:33], v[208:211], v[204:207], v[18:33]
	ds_write_b128 v162, v[106:109] offset:40960
	ds_read_b128 v[198:201], v194
	ds_read_b128 v[208:211], v194 offset:4096
	ds_read_b128 v[226:229], v196 offset:16384
	ds_read_b128 v[230:233], v196 offset:20480
	v_mfma_f32_32x32x16_bf16 v[2:17], v[212:215], v[204:207], v[2:17]
	ds_write_b128 v162, v[110:113] offset:45056
	s_waitcnt lgkmcnt(2)
	v_mfma_f32_32x32x16_bf16 v[50:65], v[226:229], v[198:201], v[50:65]
	ds_write_b128 v162, v[114:117] offset:49152
	s_waitcnt lgkmcnt(2)
	v_mfma_f32_32x32x16_bf16 v[34:49], v[230:233], v[198:201], v[34:49]
	ds_write_b128 v162, v[118:121] offset:53248
	v_mfma_f32_32x32x16_bf16 v[18:33], v[226:229], v[208:211], v[18:33]
	ds_write_b128 v162, v[122:125] offset:57344
	v_mfma_f32_32x32x16_bf16 v[2:17], v[230:233], v[208:211], v[2:17]
	ds_write_b128 v162, v[126:129] offset:61440
	s_branch .Lggc_mid
.Lggc_last:
	v_add_u32_e32 v169, v165, v163
	ds_read_b128 v[196:199], v169 offset:16384
	v_add_u32_e32 v170, v164, v163
	ds_read_b128 v[200:203], v170
	ds_read_b128 v[204:207], v170 offset:4096
	ds_read_b128 v[208:211], v169 offset:20480
	v_add_u32_e32 v171, v164, v166
	v_add_u32_e32 v172, v165, v166
	s_waitcnt lgkmcnt(0)
	v_mfma_f32_32x32x16_bf16 v[34:49], v[208:211], v[200:203], v[34:49]
	v_mfma_f32_32x32x16_bf16 v[50:65], v[196:199], v[200:203], v[50:65]
	v_mfma_f32_32x32x16_bf16 v[18:33], v[196:199], v[204:207], v[18:33]
	ds_read_b128 v[196:199], v171
	ds_read_b128 v[200:203], v171 offset:4096
	ds_read_b128 v[212:215], v172 offset:16384
	ds_read_b128 v[226:229], v172 offset:20480
	v_mfma_f32_32x32x16_bf16 v[2:17], v[208:211], v[204:207], v[2:17]
	s_waitcnt lgkmcnt(1)
	v_mfma_f32_32x32x16_bf16 v[50:65], v[212:215], v[196:199], v[50:65]
	v_add_u32_e32 v173, v164, v167
	v_add_u32_e32 v190, v165, v167
	s_waitcnt lgkmcnt(0)
	v_mfma_f32_32x32x16_bf16 v[34:49], v[226:229], v[196:199], v[34:49]
	ds_read_b128 v[196:199], v173
	ds_read_b128 v[204:207], v173 offset:4096
	v_mfma_f32_32x32x16_bf16 v[18:33], v[212:215], v[200:203], v[18:33]
	ds_read_b128 v[208:211], v190 offset:16384
	ds_read_b128 v[212:215], v190 offset:20480
	v_mfma_f32_32x32x16_bf16 v[2:17], v[226:229], v[200:203], v[2:17]
	s_waitcnt lgkmcnt(1)
	v_mfma_f32_32x32x16_bf16 v[50:65], v[208:211], v[196:199], v[50:65]
	s_waitcnt vmcnt(0)
	ds_write_b128 v162, v[98:101] offset:32768
	v_add_u32_e32 v194, v164, v168
	s_waitcnt lgkmcnt(1)
	v_mfma_f32_32x32x16_bf16 v[34:49], v[212:215], v[196:199], v[34:49]
	ds_write_b128 v162, v[102:105] offset:36864
	v_add_u32_e32 v196, v165, v168
	v_mfma_f32_32x32x16_bf16 v[18:33], v[208:211], v[204:207], v[18:33]
	ds_write_b128 v162, v[106:109] offset:40960
	ds_read_b128 v[198:201], v194
	ds_read_b128 v[208:211], v194 offset:4096
	ds_read_b128 v[226:229], v196 offset:16384
	ds_read_b128 v[230:233], v196 offset:20480
	v_mfma_f32_32x32x16_bf16 v[2:17], v[212:215], v[204:207], v[2:17]
	ds_write_b128 v162, v[110:113] offset:45056
	s_waitcnt lgkmcnt(2)
	v_mfma_f32_32x32x16_bf16 v[50:65], v[226:229], v[198:201], v[50:65]
	ds_write_b128 v162, v[114:117] offset:49152
	s_waitcnt lgkmcnt(2)
	v_mfma_f32_32x32x16_bf16 v[34:49], v[230:233], v[198:201], v[34:49]
	ds_write_b128 v162, v[118:121] offset:53248
	v_mfma_f32_32x32x16_bf16 v[18:33], v[226:229], v[208:211], v[18:33]
	ds_write_b128 v162, v[122:125] offset:57344
	v_mfma_f32_32x32x16_bf16 v[2:17], v[230:233], v[208:211], v[2:17]
	ds_write_b128 v162, v[126:129] offset:61440
; #define GL(...) GLOAD(__VA_ARGS__)
; #define SS(...) SSTORE(__VA_ARGS__)
; template <bool TRANS>
; DI void gemm_kloop(const u16* __restrict__ A, int lda, const u16* __restrict__ W, int ldw, int K, f32x16 (&acc)[2][2], char* lds) {
;     ...
;   for (int kt = 0; kt < KT; kt += 2) {
;     const bool m2 = kt + 2 < KT;
;     if (m2) { GL(SET0, (kt + 2) * 64); }
;     COMPUTE(0);
;     SS(SET1, 1);
;     __syncthreads();
;     if (m2) { GL(SET1, (kt + 3) * 64); }
;     COMPUTE(1);
;     if (m2) { SS(SET0, 0); }
;     __syncthreads();
;   }
.Lggc_mid:
	v_cndmask_b32_e64 v197, 0, 1, s[98:99]
	v_cmp_ne_u32_e64 s[42:43], 1, v197
	s_andn2_b64 vcc, exec, s[98:99]
	s_waitcnt lgkmcnt(0)
	s_barrier
	s_cbranch_vccnz .Lggc_nol1
	ds_read_b128 v[144:147], v169 offset:49152
	ds_read_b128 v[148:151], v170 offset:32768
	ds_read_b128 v[152:155], v170 offset:36864
	ds_read_b128 v[156:159], v169 offset:53248
	s_waitcnt lgkmcnt(2)
	v_mfma_f32_32x32x16_bf16 v[50:65], v[144:147], v[148:151], v[50:65]
	global_load_dwordx4 v[98:101], v0, s[6:7] offset:384
	s_waitcnt lgkmcnt(0)
	v_mfma_f32_32x32x16_bf16 v[34:49], v[156:159], v[148:151], v[34:49]
	global_load_dwordx4 v[102:105], v0, s[16:17] offset:384
	v_mfma_f32_32x32x16_bf16 v[18:33], v[144:147], v[152:155], v[18:33]
	global_load_dwordx4 v[106:109], v0, s[22:23] offset:384
	ds_read_b128 v[144:147], v171 offset:32768
	ds_read_b128 v[148:151], v171 offset:36864
	ds_read_b128 v[198:201], v172 offset:49152
	ds_read_b128 v[202:205], v172 offset:53248
	v_mfma_f32_32x32x16_bf16 v[2:17], v[156:159], v[152:155], v[2:17]
	global_load_dwordx4 v[110:113], v0, s[18:19] offset:384
	s_waitcnt lgkmcnt(1)
	v_mfma_f32_32x32x16_bf16 v[50:65], v[198:201], v[144:147], v[50:65]
	global_load_dwordx4 v[114:117], v0, s[24:25] offset:384
	s_waitcnt lgkmcnt(0)
	v_mfma_f32_32x32x16_bf16 v[34:49], v[202:205], v[144:147], v[34:49]
	global_load_dwordx4 v[118:121], v0, s[28:29] offset:384
	ds_read_b128 v[144:147], v173 offset:32768
	ds_read_b128 v[152:155], v173 offset:36864
	ds_read_b128 v[156:159], v190 offset:49152
	ds_read_b128 v[170:173], v190 offset:53248
	v_mfma_f32_32x32x16_bf16 v[18:33], v[198:201], v[148:151], v[18:33]
	global_load_dwordx4 v[122:125], v0, s[50:51]
	v_mfma_f32_32x32x16_bf16 v[2:17], v[202:205], v[148:151], v[2:17]
	global_load_dwordx4 v[126:129], v0, s[36:37] offset:384
	s_waitcnt lgkmcnt(1)
	v_mfma_f32_32x32x16_bf16 v[50:65], v[156:159], v[144:147], v[50:65]
	s_waitcnt vmcnt(8)
	ds_write_b128 v162, v[66:69]
	s_waitcnt lgkmcnt(1)
	v_mfma_f32_32x32x16_bf16 v[34:49], v[170:173], v[144:147], v[34:49]
	ds_write_b128 v162, v[70:73] offset:4096
	v_mfma_f32_32x32x16_bf16 v[18:33], v[156:159], v[152:155], v[18:33]
	ds_write_b128 v162, v[74:77] offset:8192
	ds_read_b128 v[144:147], v194 offset:32768
	ds_read_b128 v[148:151], v194 offset:36864
	ds_read_b128 v[156:159], v196 offset:49152
	ds_read_b128 v[196:199], v196 offset:53248
	v_mfma_f32_32x32x16_bf16 v[2:17], v[170:173], v[152:155], v[2:17]
	ds_write_b128 v162, v[78:81] offset:12288
	s_waitcnt lgkmcnt(2)
	v_mfma_f32_32x32x16_bf16 v[50:65], v[156:159], v[144:147], v[50:65]
	ds_write_b128 v162, v[82:85] offset:16384
	s_waitcnt lgkmcnt(2)
	v_mfma_f32_32x32x16_bf16 v[34:49], v[196:199], v[144:147], v[34:49]
	ds_write_b128 v162, v[86:89] offset:20480
	v_mfma_f32_32x32x16_bf16 v[18:33], v[156:159], v[148:151], v[18:33]
	ds_write_b128 v162, v[90:93] offset:24576
	v_mfma_f32_32x32x16_bf16 v[2:17], v[196:199], v[148:151], v[2:17]
	ds_write_b128 v162, v[94:97] offset:28672
	s_branch .LBB0_159
.Lggc_nol1:
	ds_read_b128 v[144:147], v169 offset:49152
	ds_read_b128 v[148:151], v170 offset:32768
	ds_read_b128 v[152:155], v170 offset:36864
	ds_read_b128 v[156:159], v169 offset:53248
	s_waitcnt lgkmcnt(2)
	v_mfma_f32_32x32x16_bf16 v[50:65], v[144:147], v[148:151], v[50:65]
	s_waitcnt lgkmcnt(0)
	v_mfma_f32_32x32x16_bf16 v[34:49], v[156:159], v[148:151], v[34:49]
	v_mfma_f32_32x32x16_bf16 v[18:33], v[144:147], v[152:155], v[18:33]
	ds_read_b128 v[144:147], v171 offset:32768
	ds_read_b128 v[148:151], v171 offset:36864
	ds_read_b128 v[198:201], v172 offset:49152
	ds_read_b128 v[202:205], v172 offset:53248
	v_mfma_f32_32x32x16_bf16 v[2:17], v[156:159], v[152:155], v[2:17]
	s_waitcnt lgkmcnt(1)
	v_mfma_f32_32x32x16_bf16 v[50:65], v[198:201], v[144:147], v[50:65]
	s_waitcnt lgkmcnt(0)
	v_mfma_f32_32x32x16_bf16 v[34:49], v[202:205], v[144:147], v[34:49]
	ds_read_b128 v[144:147], v173 offset:32768
	ds_read_b128 v[152:155], v173 offset:36864
	ds_read_b128 v[156:159], v190 offset:49152
	ds_read_b128 v[170:173], v190 offset:53248
	v_mfma_f32_32x32x16_bf16 v[18:33], v[198:201], v[148:151], v[18:33]
	v_mfma_f32_32x32x16_bf16 v[2:17], v[202:205], v[148:151], v[2:17]
	s_waitcnt lgkmcnt(1)
	v_mfma_f32_32x32x16_bf16 v[50:65], v[156:159], v[144:147], v[50:65]
	s_waitcnt lgkmcnt(0)
	v_mfma_f32_32x32x16_bf16 v[34:49], v[170:173], v[144:147], v[34:49]
	v_mfma_f32_32x32x16_bf16 v[18:33], v[156:159], v[152:155], v[18:33]
	ds_read_b128 v[144:147], v194 offset:32768
	ds_read_b128 v[148:151], v194 offset:36864
	ds_read_b128 v[156:159], v196 offset:49152
	ds_read_b128 v[196:199], v196 offset:53248
	v_mfma_f32_32x32x16_bf16 v[2:17], v[170:173], v[152:155], v[2:17]
	s_waitcnt lgkmcnt(1)
	v_mfma_f32_32x32x16_bf16 v[50:65], v[156:159], v[144:147], v[50:65]
	s_waitcnt lgkmcnt(0)
	v_mfma_f32_32x32x16_bf16 v[34:49], v[196:199], v[144:147], v[34:49]
	v_mfma_f32_32x32x16_bf16 v[18:33], v[156:159], v[148:151], v[18:33]
	v_mfma_f32_32x32x16_bf16 v[2:17], v[196:199], v[148:151], v[2:17]
	s_branch .LBB0_159

; #define MFMA(a, b, c) __builtin_amdgcn_mfma_f32_32x32x16_bf16((a), (b), (c), 0, 0, 0)
; template <int DQK, int DV, int TYPE>
; DI void attn_item(int layer, int qt, int head, char* lds, const Params& P) {
;     ...
;     for (int j = 0; j < NT; ++j) {
;       const int tile = TILE_OF(j);
;       const char* sb = lds + (DB ? (j & 1) * STAGE : 0);
;       constexpr int KD = 2, KRING = 3;
;       bf16x8 kr0[KRING], kr1[KRING];
;     ...
; #pragma unroll
;       for (int s = 0; s < KD; ++s) KFR(s, s)
;       __builtin_amdgcn_sched_barrier(0);
;       if constexpr (DB) {
;         char* sn = lds + ((j + 1) & 1) * STAGE;
;         if (j + 1 < NT) { ATT_SSTORE(sn); }
;         if (j + 2 < NT) { ATT_GLOAD(TILE_OF(j + 2)); }
;       } else {
;         if (j + 1 < NT) { ATT_GLOAD(TILE_OF(j + 1)); }
;       }
;       f32x16 s0, s1;
; #pragma unroll
;       for (int i = 0; i < 16; ++i) { s0[i] = 0.f; s1[i] = 0.f; }
;       {
; #pragma unroll
;         for (int s = 0; s < NS; ++s) {
;           if (s + KD < NS) KFR(s + KD, (s + KD) % KRING)
;           bf16x8 qs;
;           if constexpr (NS > NQR) { if (s < NQR) qs = qf[s < NQR ? s : 0]; else qs = *reinterpret_cast<const bf16x8*>(qpark + (s - NQR) * 4096); }
;           else qs = qf[s];
;           s0 = MFMA(kr0[s % KRING], qs, s0);
;           s1 = MFMA(kr1[s % KRING], qs, s1);
;           __builtin_amdgcn_sched_barrier(0);
;         }
.LBB0_360:
	v_add_u32_e32 v246, v228, v239
	v_add_u32_e32 v247, v228, v240
	ds_read_b128 v[66:69], v246
	ds_read_b128 v[70:73], v246 offset:12288
	ds_read_b128 v[162:165], v247
	ds_read_b128 v[166:169], v247 offset:12288
	s_waitcnt lgkmcnt(3)
	v_mfma_f32_32x32x16_bf16 v[82:97], v[66:69], v[118:121], 0
	v_add_u32_e32 v249, v228, v241
	ds_read_b128 v[170:173], v249
	ds_read_b128 v[202:205], v249 offset:12288
	s_waitcnt lgkmcnt(4)
	v_mfma_f32_32x32x16_bf16 v[66:81], v[70:73], v[118:121], 0
	s_add_u32 s6, s12, s46
	s_addc_u32 s7, s13, s47
	s_add_u32 s4, s6, 0x1583a100
	s_addc_u32 s5, s7, 0
	global_load_dwordx4 v[122:125], v0, s[4:5]
	s_waitcnt lgkmcnt(3)
	v_mfma_f32_32x32x16_bf16 v[82:97], v[162:165], v[114:117], v[82:97]
	v_add_u32_e32 v250, v228, v242
	ds_read_b128 v[162:165], v250
	ds_read_b128 v[206:209], v250 offset:12288
	s_waitcnt lgkmcnt(4)
	v_mfma_f32_32x32x16_bf16 v[66:81], v[166:169], v[114:117], v[66:81]
	s_add_u32 s4, s6, 0x15842100
	s_addc_u32 s5, s7, 0
	global_load_dwordx4 v[126:129], v0, s[4:5]
	s_waitcnt lgkmcnt(3)
	v_mfma_f32_32x32x16_bf16 v[82:97], v[170:173], v[110:113], v[82:97]
	ds_read_b128 v[166:169], v244
	ds_read_b128 v[170:173], v244 offset:12288
	s_waitcnt lgkmcnt(4)
	v_mfma_f32_32x32x16_bf16 v[66:81], v[202:205], v[110:113], v[66:81]
	s_add_u32 s4, s6, 0x1584a100
	s_addc_u32 s5, s7, 0
	global_load_dwordx4 v[130:133], v0, s[4:5]
	s_waitcnt lgkmcnt(3)
	v_mfma_f32_32x32x16_bf16 v[82:97], v[162:165], v[106:109], v[82:97]
	ds_read_b128 v[162:165], v243
	ds_read_b128 v[202:205], v243 offset:12288
	s_waitcnt lgkmcnt(4)
	v_mfma_f32_32x32x16_bf16 v[66:81], v[206:209], v[106:109], v[66:81]
	s_add_u32 s4, s6, 0x15852100
	s_addc_u32 s5, s7, 0
	s_add_u32 s6, s12, s0
	s_addc_u32 s7, s13, s1
	global_load_dwordx4 v[134:137], v0, s[4:5]
	s_waitcnt lgkmcnt(3)
	v_mfma_f32_32x32x16_bf16 v[82:97], v[166:169], v[102:105], v[82:97]
	ds_read_b128 v[166:169], v238
	ds_read_b128 v[206:209], v238 offset:12288
	s_waitcnt lgkmcnt(4)
	v_mfma_f32_32x32x16_bf16 v[66:81], v[170:173], v[102:105], v[66:81]
	s_add_u32 s4, s6, 0x12554100
	s_addc_u32 s5, s7, 0
	global_load_dwordx4 v[138:141], v200, s[4:5]
	ds_read_b128 v[214:217], v194 offset:40960
	s_waitcnt lgkmcnt(4)
	v_mfma_f32_32x32x16_bf16 v[82:97], v[162:165], v[98:101], v[82:97]
	ds_read_b128 v[162:165], v237
	ds_read_b128 v[170:173], v237 offset:12288
	s_waitcnt lgkmcnt(5)
	v_mfma_f32_32x32x16_bf16 v[66:81], v[202:205], v[98:101], v[66:81]
	s_add_u32 s4, s6, 0x12555100
	s_addc_u32 s5, s7, 0
	s_add_u32 s6, s12, s44
	s_addc_u32 s7, s13, s45
	global_load_dwordx4 v[142:145], v200, s[4:5]
	ds_read_b128 v[210:213], v194 offset:45056
	ds_read_b128 v[202:205], v236
	s_waitcnt lgkmcnt(4)
	v_mfma_f32_32x32x16_bf16 v[82:97], v[166:169], v[214:217], v[82:97]
	ds_read_b128 v[166:169], v236 offset:12288
	v_mfma_f32_32x32x16_bf16 v[66:81], v[206:209], v[214:217], v[66:81]
	s_add_u32 s4, s6, 0x1789a180
	s_addc_u32 s5, s7, 0
	global_load_dwordx4 v[146:149], v198, s[4:5]
	ds_read_b128 v[214:217], v194 offset:49152
	ds_read_b128 v[206:209], v235
	s_waitcnt lgkmcnt(4)
	v_mfma_f32_32x32x16_bf16 v[82:97], v[162:165], v[210:213], v[82:97]
	ds_read_b128 v[162:165], v235 offset:12288
	v_mfma_f32_32x32x16_bf16 v[66:81], v[170:173], v[210:213], v[66:81]
	s_add_u32 s4, s6, 0x1799e180
	s_addc_u32 s5, s7, 0
	global_load_dwordx4 v[150:153], v198, s[4:5]
	ds_read_b128 v[210:213], v194 offset:53248
	ds_read_b128 v[170:173], v234
	s_waitcnt lgkmcnt(4)
	v_mfma_f32_32x32x16_bf16 v[82:97], v[202:205], v[214:217], v[82:97]
	ds_read_b128 v[202:205], v234 offset:12288
	v_mfma_f32_32x32x16_bf16 v[66:81], v[166:169], v[214:217], v[66:81]
	s_add_u32 s4, s6, 0x17aa2180
	s_addc_u32 s5, s7, 0
	global_load_dwordx4 v[154:157], v198, s[4:5]
	ds_read_b128 v[214:217], v194 offset:57344
	ds_read_b128 v[166:169], v233
	s_waitcnt lgkmcnt(4)
	v_mfma_f32_32x32x16_bf16 v[82:97], v[206:209], v[210:213], v[82:97]
	ds_read_b128 v[206:209], v233 offset:12288
	v_mfma_f32_32x32x16_bf16 v[66:81], v[162:165], v[210:213], v[66:81]
	s_add_u32 s4, s6, 0x17ba6180
	s_addc_u32 s5, s7, 0
	global_load_dwordx4 v[158:161], v198, s[4:5]
	ds_read_b128 v[210:213], v194 offset:61440
	s_waitcnt lgkmcnt(3)
	v_mfma_f32_32x32x16_bf16 v[82:97], v[170:173], v[214:217], v[82:97]
	v_mfma_f32_32x32x16_bf16 v[66:81], v[202:205], v[214:217], v[66:81]
	s_waitcnt lgkmcnt(0)
; template <int DQK, int DV, int TYPE>
; DI void attn_item(int layer, int qt, int head, char* lds, const Params& P) {
;     ...
;       const char* vb0 = sb + VOFF + r * 128;
;     ...
;       constexpr int VD = 3;
;       bf16x8 vr[8];
; #pragma unroll
;       for (int g = 0; g < VD; ++g) vr[g] = VFRAG(g >> 2, g & 3);
;       if (TYPE == 2 && latent && j < na) {
;         const int kb0 = tile * 64 - qrow;
; #pragma unroll
;         for (int i = 0; i < 16; ++i) {
;           const int d0 = kb0 + crow(i, h), d1 = d0 + 32;
;           if (d0 > 128 || d0 < -128) s0[i] = -1e30f;
;           if (d1 > 128 || d1 < -128) s1[i] = -1e30f;
;         }
;       }
;       const float tm0 = vmax3w(s0[0], s0[1], s0[2], s1[0]);
;       const float tm1 = vmax3d(s0[3], s0[4], s0[5], tm0), tm2 = vmax3d(s0[6], s0[7], s0[8], tm0), tm3 = vmax3d(s0[9], s0[10], s0[11], tm0);
;       const float tm4 = vmax3d(s0[12], s0[13], s0[14], tm0);
;       const float tm5 = vmax3d4(s1[0], s1[1], s1[2], tm1, tm2, tm3, tm4), tm6 = vmax3d(s1[3], s1[4], s1[5], tm5), tm7 = vmax3d(s1[6], s1[7], s1[8], tm5);
;       const float tm8 = vmax3d(s1[9], s1[10], s1[11], tm5), tm9 = vmax3d(s1[12], s1[13], s1[14], tm5), tma = vmax3d(s0[15], s1[15], tm0, tm5), tmb = vmax3(tm1, tm2, tm3);
;       const float tmc = vmax3(tm4, tm5, tm6), tmd = vmax3(tm7, tm8, tm9);
;       float tmax = xhalf_max(vmax3(vmax3(tma, tmb, tmc), tmd, tmd));
;       const float mnew = fmaxf(m_run, tmax);
;       const float alpha = __builtin_amdgcn_exp2f((m_run - mnew) * C);
;       m_run = mnew;
;       const float mc = -mnew * C;
;       float pa = 0.f, pb = 0.f, pc = 0.f, pd = 0.f;
; #pragma unroll
;       for (int i = 0; i < 16; i += 2) {
;         s0[i] = __builtin_amdgcn_exp2f(fmaf(s0[i], C, mc)); pa += s0[i];
;         s0[i + 1] = __builtin_amdgcn_exp2f(fmaf(s0[i + 1], C, mc)); pb += s0[i + 1];
;       }
; #pragma unroll
;       for (int i = 0; i < 16; i += 2) {
;         s1[i] = __builtin_amdgcn_exp2f(fmaf(s1[i], C, mc)); pc += s1[i];
;         s1[i + 1] = __builtin_amdgcn_exp2f(fmaf(s1[i + 1], C, mc)); pd += s1[i + 1];
;       }
;       const float ps = xhalf_sum((pa + pb) + (pc + pd));
;       l_run = l_run * alpha + ps;
;       if (__any(alpha != 1.f)) {
; #pragma unroll
;         for (int d = 0; d < NDV; ++d)
; #pragma unroll
;           for (int i = 0; i < 16; ++i) oacc[d][i] *= alpha;
;       }
	v_mfma_f32_32x32x16_bf16 v[82:97], v[166:169], v[210:213], v[82:97]
	v_add_u32_e32 v231, v232, v239
	v_add_u32_e32 v229, v232, v241
	v_add_u32_e32 v230, v232, v240
	ds_read_b128 v[170:173], v231 offset:24576
	ds_read_b128 v[166:169], v230 offset:24576
	ds_read_b128 v[162:165], v229 offset:24576
	v_mfma_f32_32x32x16_bf16 v[66:81], v[206:209], v[210:213], v[66:81]
	s_nop 15
	v_max3_f32 v202, v82, v83, v84
	s_nop 0
	v_max3_f32 v203, v85, v86, v87
	v_max3_f32 v204, v88, v89, v90
	v_max3_f32 v205, v91, v92, v93
	v_max3_f32 v206, v94, v95, v96
	s_nop 0
	v_max3_f32 v207, v66, v67, v68
	v_max3_f32 v203, v203, v204, v205
	s_nop 0
	v_max3_f32 v202, v97, v81, v202
	v_max3_f32 v208, v69, v70, v71
	v_max3_f32 v209, v72, v73, v74
	v_max3_f32 v210, v75, v76, v77
	v_max3_f32 v211, v78, v79, v80
	s_nop 0
	v_max3_f32 v204, v206, v207, v208
	v_max3_f32 v205, v209, v210, v211
	s_nop 0
	v_max3_f32 v202, v202, v203, v204
	s_nop 0
	v_max3_f32 v202, v202, v205, v205
	s_nop 0
	v_mov_b32_e32 v203, v202
	s_nop 1
	v_permlane32_swap_b32_e32 v202, v203
	v_max3_f32 v220, v248, v202, v203
	v_sub_f32_e32 v202, v248, v220
	v_mov_b32_e32 v248, v220
	v_mul_f32_e32 v220, 0xbdd53b94, v248
	v_fmamk_f32 v82, v82, 0x3dd53b94, v220
	v_mul_f32_e32 v245, 0x3dd53b94, v202
	v_exp_f32_e32 v202, v82
	v_fmamk_f32 v82, v83, 0x3dd53b94, v220
	v_exp_f32_e32 v204, v82
	v_fmamk_f32 v82, v84, 0x3dd53b94, v220
	v_fmamk_f32 v66, v66, 0x3dd53b94, v220
	v_exp_f32_e32 v206, v82
	v_fmamk_f32 v82, v85, 0x3dd53b94, v220
	v_exp_f32_e32 v203, v66
	v_fmamk_f32 v66, v67, 0x3dd53b94, v220
	v_exp_f32_e32 v208, v82
	v_fmamk_f32 v82, v86, 0x3dd53b94, v220
	v_fmamk_f32 v83, v91, 0x3dd53b94, v220
	v_exp_f32_e32 v205, v66
	v_fmamk_f32 v66, v68, 0x3dd53b94, v220
	v_exp_f32_e32 v210, v82
	v_fmamk_f32 v82, v87, 0x3dd53b94, v220
	v_exp_f32_e32 v84, v83
	v_fmamk_f32 v83, v92, 0x3dd53b94, v220
	v_exp_f32_e32 v207, v66
	v_fmamk_f32 v66, v69, 0x3dd53b94, v220
	v_exp_f32_e32 v212, v82
	v_fmamk_f32 v82, v88, 0x3dd53b94, v220
	v_exp_f32_e32 v86, v83
	v_fmamk_f32 v83, v93, 0x3dd53b94, v220
	v_exp_f32_e32 v209, v66
	v_fmamk_f32 v66, v70, 0x3dd53b94, v220
	v_exp_f32_e32 v214, v82
	v_fmamk_f32 v82, v89, 0x3dd53b94, v220
	v_exp_f32_e32 v88, v83
	v_fmamk_f32 v83, v94, 0x3dd53b94, v220
	v_exp_f32_e32 v211, v66
	v_fmamk_f32 v66, v71, 0x3dd53b94, v220
	v_exp_f32_e32 v216, v82
	v_fmamk_f32 v82, v90, 0x3dd53b94, v220
	v_exp_f32_e32 v90, v83
	v_fmamk_f32 v83, v95, 0x3dd53b94, v220
	v_exp_f32_e32 v213, v66
	v_fmamk_f32 v66, v72, 0x3dd53b94, v220
	v_exp_f32_e32 v92, v83
	v_fmamk_f32 v83, v96, 0x3dd53b94, v220
	v_exp_f32_e32 v215, v66
	v_fmamk_f32 v66, v73, 0x3dd53b94, v220
	v_exp_f32_e32 v94, v83
	v_fmamk_f32 v83, v97, 0x3dd53b94, v220
	v_exp_f32_e32 v217, v66
	v_fmamk_f32 v66, v74, 0x3dd53b94, v220
	v_exp_f32_e32 v96, v83
	v_exp_f32_e32 v83, v66
	v_fmamk_f32 v66, v75, 0x3dd53b94, v220
	v_exp_f32_e32 v85, v66
	v_fmamk_f32 v66, v76, 0x3dd53b94, v220
	v_exp_f32_e32 v87, v66
	v_fmamk_f32 v66, v77, 0x3dd53b94, v220
	v_exp_f32_e32 v82, v82
	v_exp_f32_e32 v89, v66
	v_fmamk_f32 v66, v78, 0x3dd53b94, v220
	v_pk_add_f32 v[68:69], v[204:205], 0 op_sel_hi:[1,0]
	v_pk_add_f32 v[70:71], v[202:203], 0 op_sel_hi:[1,0]
	v_exp_f32_e32 v91, v66
	v_fmamk_f32 v66, v79, 0x3dd53b94, v220
	v_pk_add_f32 v[68:69], v[208:209], v[68:69]
	v_pk_add_f32 v[70:71], v[206:207], v[70:71]
	v_exp_f32_e32 v93, v66
	v_fmamk_f32 v66, v80, 0x3dd53b94, v220
	v_fmac_f32_e32 v220, 0x3dd53b94, v81
	v_pk_add_f32 v[68:69], v[212:213], v[68:69]
	v_pk_add_f32 v[70:71], v[210:211], v[70:71]
	v_exp_f32_e32 v95, v66
	v_exp_f32_e32 v97, v220
	v_pk_add_f32 v[68:69], v[216:217], v[68:69]
	v_pk_add_f32 v[70:71], v[214:215], v[70:71]
	v_pk_add_f32 v[68:69], v[84:85], v[68:69]
	v_pk_add_f32 v[70:71], v[82:83], v[70:71]
	v_pk_add_f32 v[68:69], v[88:89], v[68:69]
	v_pk_add_f32 v[70:71], v[86:87], v[70:71]
	v_pk_add_f32 v[68:69], v[92:93], v[68:69]
	v_pk_add_f32 v[70:71], v[90:91], v[70:71]
	v_exp_f32_e32 v66, v245
	v_pk_add_f32 v[68:69], v[96:97], v[68:69]
	v_pk_add_f32 v[70:71], v[94:95], v[70:71]
	v_cmp_neq_f32_e32 vcc, 1.0, v66
	v_pk_add_f32 v[68:69], v[70:71], v[68:69]
	s_nop 0
	v_pk_add_f32 v[68:69], v[68:69], v[68:69] op_sel:[0,1] op_sel_hi:[1,0]
	s_nop 0
	v_mov_b32_e32 v67, v68
	s_nop 1
	v_permlane32_swap_b32_e32 v68, v67
	s_cbranch_vccz .LBB0_362
	v_pk_mul_f32 v[64:65], v[64:65], v[66:67] op_sel_hi:[1,0]
	v_pk_mul_f32 v[62:63], v[62:63], v[66:67] op_sel_hi:[1,0]
	v_pk_mul_f32 v[60:61], v[60:61], v[66:67] op_sel_hi:[1,0]
	v_pk_mul_f32 v[58:59], v[58:59], v[66:67] op_sel_hi:[1,0]
	v_pk_mul_f32 v[56:57], v[56:57], v[66:67] op_sel_hi:[1,0]
	v_pk_mul_f32 v[54:55], v[54:55], v[66:67] op_sel_hi:[1,0]
	v_pk_mul_f32 v[52:53], v[52:53], v[66:67] op_sel_hi:[1,0]
	v_pk_mul_f32 v[50:51], v[50:51], v[66:67] op_sel_hi:[1,0]
	v_pk_mul_f32 v[48:49], v[48:49], v[66:67] op_sel_hi:[1,0]
	v_pk_mul_f32 v[46:47], v[46:47], v[66:67] op_sel_hi:[1,0]
	v_pk_mul_f32 v[44:45], v[44:45], v[66:67] op_sel_hi:[1,0]
	v_pk_mul_f32 v[42:43], v[42:43], v[66:67] op_sel_hi:[1,0]
	v_pk_mul_f32 v[40:41], v[40:41], v[66:67] op_sel_hi:[1,0]
	v_pk_mul_f32 v[38:39], v[38:39], v[66:67] op_sel_hi:[1,0]
	v_pk_mul_f32 v[36:37], v[36:37], v[66:67] op_sel_hi:[1,0]
	v_pk_mul_f32 v[34:35], v[34:35], v[66:67] op_sel_hi:[1,0]
	v_pk_mul_f32 v[32:33], v[32:33], v[66:67] op_sel_hi:[1,0]
	v_pk_mul_f32 v[30:31], v[30:31], v[66:67] op_sel_hi:[1,0]
	v_pk_mul_f32 v[28:29], v[28:29], v[66:67] op_sel_hi:[1,0]
	v_pk_mul_f32 v[26:27], v[26:27], v[66:67] op_sel_hi:[1,0]
	v_pk_mul_f32 v[24:25], v[24:25], v[66:67] op_sel_hi:[1,0]
	v_pk_mul_f32 v[22:23], v[22:23], v[66:67] op_sel_hi:[1,0]
	v_pk_mul_f32 v[20:21], v[20:21], v[66:67] op_sel_hi:[1,0]
	v_pk_mul_f32 v[18:19], v[18:19], v[66:67] op_sel_hi:[1,0]
	v_pk_mul_f32 v[16:17], v[16:17], v[66:67] op_sel_hi:[1,0]
	v_pk_mul_f32 v[14:15], v[14:15], v[66:67] op_sel_hi:[1,0]
	v_pk_mul_f32 v[12:13], v[12:13], v[66:67] op_sel_hi:[1,0]
	v_pk_mul_f32 v[10:11], v[10:11], v[66:67] op_sel_hi:[1,0]
	v_pk_mul_f32 v[8:9], v[8:9], v[66:67] op_sel_hi:[1,0]
	v_pk_mul_f32 v[6:7], v[6:7], v[66:67] op_sel_hi:[1,0]
	v_pk_mul_f32 v[4:5], v[4:5], v[66:67] op_sel_hi:[1,0]
	v_pk_mul_f32 v[2:3], v[2:3], v[66:67] op_sel_hi:[1,0]

; template <int DQK, int DV, int TYPE>
; DI void attn_item(int layer, int qt, int head, char* lds, const Params& P) {
;     ...
;     for (int j = 0; j < NT; ++j) {
;       const int tile = TILE_OF(j);
;       const char* sb = lds + (DB ? (j & 1) * STAGE : 0);
;       constexpr int KD = 2, KRING = 3;
;       bf16x8 kr0[KRING], kr1[KRING];
;     ...
; #pragma unroll
;       for (int s = 0; s < KD; ++s) KFR(s, s)
;       __builtin_amdgcn_sched_barrier(0);
;       if constexpr (DB) {
;         char* sn = lds + ((j + 1) & 1) * STAGE;
;         if (j + 1 < NT) { ATT_SSTORE(sn); }
.LBB0_372:
	s_add_i32 s16, s5, -1
	s_bitcmp1_b32 s16, 0
	s_cselect_b32 s14, 0x6000, 0
	v_add_u32_e32 v0, s14, v168
	v_add_u32_e32 v15, v0, v164
	v_add_u32_e32 v14, v0, v165
	ds_read_b128 v[80:83], v15
	ds_read_b128 v[10:13], v15 offset:4096
	ds_read_b128 v[6:9], v14
	ds_read_b128 v[2:5], v14 offset:4096
	s_bitcmp1_b32 s5, 0
	s_cselect_b32 s14, 0x6000, 0
	s_add_i32 s14, s14, 0
	v_add_u32_e32 v194, s14, v162
	s_waitcnt vmcnt(0)
	s_waitcnt lgkmcnt(3)
	v_mfma_f32_32x32x16_bf16 v[96:111], v[80:83], v[124:127], 0
	ds_write_b128 v194, v[128:131]
	v_add_u32_e32 v172, v0, v166
	ds_read_b128 v[196:199], v172
	ds_read_b128 v[200:203], v172 offset:4096
	s_waitcnt lgkmcnt(5)
	v_mfma_f32_32x32x16_bf16 v[80:95], v[10:13], v[124:127], 0
	ds_write_b128 v194, v[132:135] offset:4096
	s_waitcnt lgkmcnt(5)
	v_mfma_f32_32x32x16_bf16 v[96:111], v[6:9], v[120:123], v[96:111]
	ds_write_b128 v194, v[136:139] offset:8192
	v_add_u32_e32 v173, v0, v167
	ds_read_b128 v[6:9], v173
	ds_read_b128 v[204:207], v173 offset:4096
	s_waitcnt lgkmcnt(7)
	v_mfma_f32_32x32x16_bf16 v[80:95], v[2:5], v[120:123], v[80:95]
	ds_write_b128 v194, v[140:143] offset:12288
	s_waitcnt lgkmcnt(6)
	v_mfma_f32_32x32x16_bf16 v[96:111], v[196:199], v[116:119], v[96:111]
	ds_write_b128 v194, v[144:147] offset:16384
	s_waitcnt lgkmcnt(6)
	v_mfma_f32_32x32x16_bf16 v[80:95], v[200:203], v[116:119], v[80:95]
	ds_write_b128 v194, v[148:151] offset:20480
	s_waitcnt lgkmcnt(4)
	v_mfma_f32_32x32x16_bf16 v[96:111], v[6:9], v[112:115], v[96:111]
	ds_read_b128 v[10:13], v15 offset:8192
	ds_read_b128 v[6:9], v14 offset:8192
	ds_read_b128 v[2:5], v172 offset:8192
	s_waitcnt lgkmcnt(6)
	v_mfma_f32_32x32x16_bf16 v[80:95], v[204:207], v[112:115], v[80:95]
	s_cmpk_gt_u32 s16, 0x101
	s_cbranch_scc1 .Lt0w_skip_a
	s_add_u32 s18, s12, s6
	s_addc_u32 s19, s13, s7
	s_add_u32 s16, s18, 0x9f82100
	s_addc_u32 s17, s19, 0
	global_load_dwordx4 v[128:131], v154, s[16:17]
	s_add_u32 s16, s18, 0x9f92100
	s_addc_u32 s17, s19, 0
	s_add_u32 s18, s12, s0
	s_addc_u32 s19, s13, s1
	global_load_dwordx4 v[132:135], v154, s[16:17]
	s_add_u32 s16, s18, 0xbfc2200
	s_addc_u32 s17, s19, 0
	global_load_dwordx4 v[136:139], v152, s[16:17]
	s_add_u32 s16, s18, 0xc0c6200
	s_addc_u32 s17, s19, 0
	global_load_dwordx4 v[140:143], v152, s[16:17]
	s_add_u32 s16, s18, 0xc1ca200
	s_addc_u32 s17, s19, 0
	global_load_dwordx4 v[144:147], v152, s[16:17]
	s_add_u32 s16, s18, 0xc2ce200
	s_addc_u32 s17, s19, 0
	global_load_dwordx4 v[148:151], v152, s[16:17]

; #define GL(...) GLOAD(__VA_ARGS__)
; #define SS(...) SSTORE(__VA_ARGS__)
; template <bool TRANS>
; DI void gemm_kloop(const u16* __restrict__ A, int lda, const u16* __restrict__ W, int ldw, int K, f32x16 (&acc)[2][2], char* lds) {
;     ...
;   GL(SET0, 0);
;   SS(SET0, 0);
;   GL(SET1, 64);
;   __syncthreads();
;   for (int kt = 0; kt < KT; kt += 2) {
;     const bool m2 = kt + 2 < KT;
;     if (m2) { GL(SET0, (kt + 2) * 64); }
;     COMPUTE(0);
;     SS(SET1, 1);
;     __syncthreads();
;     if (m2) { GL(SET1, (kt + 3) * 64); }
;     COMPUTE(1);
;     if (m2) { SS(SET0, 0); }
;     __syncthreads();
;   }
.LBB0_465:
	s_cmp_lt_u32 s2, s14
	s_cselect_b64 s[68:69], -1, 0
	s_cmp_ge_u32 s2, s14
	s_cselect_b64 s[30:31], -1, 0
	s_and_b64 vcc, exec, s[30:31]
	s_cbranch_vccnz .Lgga_last
	v_add_u32_e32 v169, v165, v143
	ds_read_b128 v[196:199], v169 offset:16384
	v_add_u32_e32 v170, v164, v143
	ds_read_b128 v[200:203], v170
	ds_read_b128 v[204:207], v170 offset:4096
	ds_read_b128 v[208:211], v169 offset:20480
	v_add_u32_e32 v171, v164, v166
	v_add_u32_e32 v172, v165, v166
	s_waitcnt lgkmcnt(0)
	v_mfma_f32_32x32x16_bf16 v[50:65], v[208:211], v[200:203], v[50:65]
	global_load_dwordx4 v[66:69], v0, s[28:29] offset:256
	v_mfma_f32_32x32x16_bf16 v[34:49], v[196:199], v[200:203], v[34:49]
	global_load_dwordx4 v[70:73], v0, s[22:23] offset:256
	v_mfma_f32_32x32x16_bf16 v[2:17], v[196:199], v[204:207], v[2:17]
	global_load_dwordx4 v[74:77], v0, s[50:51] offset:256
	ds_read_b128 v[196:199], v171
	ds_read_b128 v[200:203], v171 offset:4096
	ds_read_b128 v[212:215], v172 offset:16384
	ds_read_b128 v[226:229], v172 offset:20480
	v_mfma_f32_32x32x16_bf16 v[18:33], v[208:211], v[204:207], v[18:33]
	global_load_dwordx4 v[78:81], v0, s[98:99] offset:256
	s_waitcnt lgkmcnt(1)
	v_mfma_f32_32x32x16_bf16 v[34:49], v[212:215], v[196:199], v[34:49]
	global_load_dwordx4 v[82:85], v0, s[24:25] offset:256
	v_add_u32_e32 v173, v164, v167
	v_add_u32_e32 v190, v165, v167
	s_waitcnt lgkmcnt(0)
	v_mfma_f32_32x32x16_bf16 v[50:65], v[226:229], v[196:199], v[50:65]
	global_load_dwordx4 v[86:89], v0, s[6:7] offset:256
	ds_read_b128 v[196:199], v173
	ds_read_b128 v[204:207], v173 offset:4096
	v_mfma_f32_32x32x16_bf16 v[2:17], v[212:215], v[200:203], v[2:17]
	global_load_dwordx4 v[90:93], v0, s[46:47] offset:256
	ds_read_b128 v[208:211], v190 offset:16384
	ds_read_b128 v[212:215], v190 offset:20480
	v_mfma_f32_32x32x16_bf16 v[18:33], v[226:229], v[200:203], v[18:33]
	global_load_dwordx4 v[94:97], v0, s[16:17] offset:256
	s_waitcnt lgkmcnt(1)
	v_mfma_f32_32x32x16_bf16 v[34:49], v[208:211], v[196:199], v[34:49]
	s_waitcnt vmcnt(8)
	ds_write_b128 v141, v[98:101] offset:32768
	v_add_u32_e32 v194, v164, v168
	s_waitcnt lgkmcnt(1)
	v_mfma_f32_32x32x16_bf16 v[50:65], v[212:215], v[196:199], v[50:65]
	ds_write_b128 v141, v[102:105] offset:36864
	v_add_u32_e32 v196, v165, v168
	v_mfma_f32_32x32x16_bf16 v[2:17], v[208:211], v[204:207], v[2:17]
	ds_write_b128 v141, v[110:113] offset:40960
	ds_read_b128 v[198:201], v194
	ds_read_b128 v[208:211], v194 offset:4096
	ds_read_b128 v[226:229], v196 offset:16384
	ds_read_b128 v[230:233], v196 offset:20480
	v_mfma_f32_32x32x16_bf16 v[18:33], v[212:215], v[204:207], v[18:33]
	ds_write_b128 v141, v[106:109] offset:45056
	s_waitcnt lgkmcnt(2)
	v_mfma_f32_32x32x16_bf16 v[34:49], v[226:229], v[198:201], v[34:49]
	ds_write_b128 v141, v[114:117] offset:49152
	s_waitcnt lgkmcnt(2)
	v_mfma_f32_32x32x16_bf16 v[50:65], v[230:233], v[198:201], v[50:65]
	ds_write_b128 v141, v[122:125] offset:53248
	v_mfma_f32_32x32x16_bf16 v[2:17], v[226:229], v[208:211], v[2:17]
	ds_write_b128 v141, v[118:121] offset:57344
	v_mfma_f32_32x32x16_bf16 v[18:33], v[230:233], v[208:211], v[18:33]
	ds_write_b128 v141, v[126:129] offset:61440
	s_branch .Lgga_mid
; #define GL(...) GLOAD(__VA_ARGS__)
; #define SS(...) SSTORE(__VA_ARGS__)
; template <bool TRANS>
; DI void gemm_kloop(const u16* __restrict__ A, int lda, const u16* __restrict__ W, int ldw, int K, f32x16 (&acc)[2][2], char* lds) {
;     ...
;   GL(SET0, 0);
;   SS(SET0, 0);
;   GL(SET1, 64);
;   __syncthreads();
;   for (int kt = 0; kt < KT; kt += 2) {
;     const bool m2 = kt + 2 < KT;
;     if (m2) { GL(SET0, (kt + 2) * 64); }
;     COMPUTE(0);
;     SS(SET1, 1);
;     __syncthreads();
;     if (m2) { GL(SET1, (kt + 3) * 64); }
;     COMPUTE(1);
;     if (m2) { SS(SET0, 0); }
;     __syncthreads();
;   }
.Lgga_last:
	v_add_u32_e32 v169, v165, v143
	ds_read_b128 v[196:199], v169 offset:16384
	v_add_u32_e32 v170, v164, v143
	ds_read_b128 v[200:203], v170
	ds_read_b128 v[204:207], v170 offset:4096
	ds_read_b128 v[208:211], v169 offset:20480
	v_add_u32_e32 v171, v164, v166
	v_add_u32_e32 v172, v165, v166
	s_waitcnt lgkmcnt(0)
	v_mfma_f32_32x32x16_bf16 v[50:65], v[208:211], v[200:203], v[50:65]
	v_mfma_f32_32x32x16_bf16 v[34:49], v[196:199], v[200:203], v[34:49]
	v_mfma_f32_32x32x16_bf16 v[2:17], v[196:199], v[204:207], v[2:17]
	ds_read_b128 v[196:199], v171
	ds_read_b128 v[200:203], v171 offset:4096
	ds_read_b128 v[212:215], v172 offset:16384
	ds_read_b128 v[226:229], v172 offset:20480
	v_mfma_f32_32x32x16_bf16 v[18:33], v[208:211], v[204:207], v[18:33]
	s_waitcnt lgkmcnt(1)
	v_mfma_f32_32x32x16_bf16 v[34:49], v[212:215], v[196:199], v[34:49]
	v_add_u32_e32 v173, v164, v167
	v_add_u32_e32 v190, v165, v167
	s_waitcnt lgkmcnt(0)
	v_mfma_f32_32x32x16_bf16 v[50:65], v[226:229], v[196:199], v[50:65]
	ds_read_b128 v[196:199], v173
	ds_read_b128 v[204:207], v173 offset:4096
	v_mfma_f32_32x32x16_bf16 v[2:17], v[212:215], v[200:203], v[2:17]
	ds_read_b128 v[208:211], v190 offset:16384
	ds_read_b128 v[212:215], v190 offset:20480
	v_mfma_f32_32x32x16_bf16 v[18:33], v[226:229], v[200:203], v[18:33]
	s_waitcnt lgkmcnt(1)
	v_mfma_f32_32x32x16_bf16 v[34:49], v[208:211], v[196:199], v[34:49]
	s_waitcnt vmcnt(0)
	ds_write_b128 v141, v[98:101] offset:32768
	v_add_u32_e32 v194, v164, v168
	s_waitcnt lgkmcnt(1)
	v_mfma_f32_32x32x16_bf16 v[50:65], v[212:215], v[196:199], v[50:65]
	ds_write_b128 v141, v[102:105] offset:36864
	v_add_u32_e32 v196, v165, v168
	v_mfma_f32_32x32x16_bf16 v[2:17], v[208:211], v[204:207], v[2:17]
	ds_write_b128 v141, v[110:113] offset:40960
	ds_read_b128 v[198:201], v194
	ds_read_b128 v[208:211], v194 offset:4096
	ds_read_b128 v[226:229], v196 offset:16384
	ds_read_b128 v[230:233], v196 offset:20480
	v_mfma_f32_32x32x16_bf16 v[18:33], v[212:215], v[204:207], v[18:33]
	ds_write_b128 v141, v[106:109] offset:45056
	s_waitcnt lgkmcnt(2)
	v_mfma_f32_32x32x16_bf16 v[34:49], v[226:229], v[198:201], v[34:49]
	ds_write_b128 v141, v[114:117] offset:49152
	s_waitcnt lgkmcnt(2)
	v_mfma_f32_32x32x16_bf16 v[50:65], v[230:233], v[198:201], v[50:65]
	ds_write_b128 v141, v[122:125] offset:53248
	v_mfma_f32_32x32x16_bf16 v[2:17], v[226:229], v[208:211], v[2:17]
	ds_write_b128 v141, v[118:121] offset:57344
	v_mfma_f32_32x32x16_bf16 v[18:33], v[230:233], v[208:211], v[18:33]
	ds_write_b128 v141, v[126:129] offset:61440
.Lgga_mid:
	v_cndmask_b32_e64 v197, 0, 1, s[68:69]
	v_cmp_ne_u32_e64 s[42:43], 1, v197
	s_andn2_b64 vcc, exec, s[68:69]
	s_waitcnt lgkmcnt(0)
	s_barrier
	s_cbranch_vccnz .Lgga_nol1
	ds_read_b128 v[144:147], v169 offset:49152
	ds_read_b128 v[148:151], v170 offset:32768
	ds_read_b128 v[152:155], v170 offset:36864
	ds_read_b128 v[156:159], v169 offset:53248
	s_waitcnt lgkmcnt(2)
	v_mfma_f32_32x32x16_bf16 v[34:49], v[144:147], v[148:151], v[34:49]
	global_load_dwordx4 v[98:101], v0, s[28:29] offset:384
	s_waitcnt lgkmcnt(0)
	v_mfma_f32_32x32x16_bf16 v[50:65], v[156:159], v[148:151], v[50:65]
	global_load_dwordx4 v[102:105], v0, s[22:23] offset:384
	v_mfma_f32_32x32x16_bf16 v[2:17], v[144:147], v[152:155], v[2:17]
	global_load_dwordx4 v[110:113], v0, s[50:51] offset:384
	ds_read_b128 v[144:147], v171 offset:32768
	ds_read_b128 v[148:151], v171 offset:36864
	ds_read_b128 v[198:201], v172 offset:49152
	ds_read_b128 v[202:205], v172 offset:53248
	v_mfma_f32_32x32x16_bf16 v[18:33], v[156:159], v[152:155], v[18:33]
	global_load_dwordx4 v[106:109], v0, s[98:99] offset:384
	s_waitcnt lgkmcnt(1)
	v_mfma_f32_32x32x16_bf16 v[34:49], v[198:201], v[144:147], v[34:49]
	global_load_dwordx4 v[114:117], v0, s[24:25] offset:384
	s_waitcnt lgkmcnt(0)
	v_mfma_f32_32x32x16_bf16 v[50:65], v[202:205], v[144:147], v[50:65]
	global_load_dwordx4 v[122:125], v0, s[6:7] offset:384
	ds_read_b128 v[144:147], v173 offset:32768
	ds_read_b128 v[152:155], v173 offset:36864
	ds_read_b128 v[156:159], v190 offset:49152
	ds_read_b128 v[170:173], v190 offset:53248
	v_mfma_f32_32x32x16_bf16 v[2:17], v[198:201], v[148:151], v[2:17]
	global_load_dwordx4 v[118:121], v0, s[46:47] offset:384
	v_mfma_f32_32x32x16_bf16 v[18:33], v[202:205], v[148:151], v[18:33]
	global_load_dwordx4 v[126:129], v0, s[16:17] offset:384
	s_waitcnt lgkmcnt(1)
	v_mfma_f32_32x32x16_bf16 v[34:49], v[156:159], v[144:147], v[34:49]
	s_waitcnt vmcnt(8)
	ds_write_b128 v141, v[66:69]
	s_waitcnt lgkmcnt(1)
	v_mfma_f32_32x32x16_bf16 v[50:65], v[170:173], v[144:147], v[50:65]
	ds_write_b128 v141, v[70:73] offset:4096
	v_mfma_f32_32x32x16_bf16 v[2:17], v[156:159], v[152:155], v[2:17]
	ds_write_b128 v141, v[74:77] offset:8192
	ds_read_b128 v[144:147], v194 offset:32768
	ds_read_b128 v[148:151], v194 offset:36864
	ds_read_b128 v[156:159], v196 offset:49152
	ds_read_b128 v[196:199], v196 offset:53248
	v_mfma_f32_32x32x16_bf16 v[18:33], v[170:173], v[152:155], v[18:33]
	ds_write_b128 v141, v[78:81] offset:12288
	s_waitcnt lgkmcnt(2)
	v_mfma_f32_32x32x16_bf16 v[34:49], v[156:159], v[144:147], v[34:49]
	ds_write_b128 v141, v[82:85] offset:16384
	s_waitcnt lgkmcnt(2)
	v_mfma_f32_32x32x16_bf16 v[50:65], v[196:199], v[144:147], v[50:65]
	ds_write_b128 v141, v[86:89] offset:20480
	v_mfma_f32_32x32x16_bf16 v[2:17], v[156:159], v[148:151], v[2:17]
	ds_write_b128 v141, v[90:93] offset:24576
	v_mfma_f32_32x32x16_bf16 v[18:33], v[196:199], v[148:151], v[18:33]
	ds_write_b128 v141, v[94:97] offset:28672
	s_branch .LBB0_464

; #define GL(...) GLOAD(__VA_ARGS__)
; #define SS(...) SSTORE(__VA_ARGS__)
; template <bool TRANS>
; DI void gemm_kloop(const u16* __restrict__ A, int lda, const u16* __restrict__ W, int ldw, int K, f32x16 (&acc)[2][2], char* lds) {
;     ...
;   GL(SET0, 0);
;   SS(SET0, 0);
;   GL(SET1, 64);
;   __syncthreads();
;   for (int kt = 0; kt < KT; kt += 2) {
;     const bool m2 = kt + 2 < KT;
;     if (m2) { GL(SET0, (kt + 2) * 64); }
;     COMPUTE(0);
;     SS(SET1, 1);
;     __syncthreads();
;     if (m2) { GL(SET1, (kt + 3) * 64); }
;     COMPUTE(1);
;     if (m2) { SS(SET0, 0); }
;     __syncthreads();
;   }
.LBB0_477:
	s_cmp_lt_u32 s2, s14
	s_cselect_b64 s[36:37], -1, 0
	s_cmp_ge_u32 s2, s14
	s_cselect_b64 s[30:31], -1, 0
	s_and_b64 vcc, exec, s[30:31]
	s_cbranch_vccnz .Lggb_last
	v_add_u32_e32 v169, v164, v143
	ds_read_b128 v[196:199], v169
	v_add_u32_e32 v170, v165, v143
	ds_read_b128 v[200:203], v170 offset:16384
	ds_read_b128 v[204:207], v169 offset:4096
	ds_read_b128 v[208:211], v170 offset:20480
	v_add_u32_e32 v171, v164, v166
	s_waitcnt lgkmcnt(1)
	v_mfma_f32_32x32x16_bf16 v[2:17], v[204:207], v[200:203], v[2:17]
	global_load_dwordx4 v[66:69], v0, s[28:29] offset:256
	v_add_u32_e32 v172, v165, v166
	v_mfma_f32_32x32x16_bf16 v[34:49], v[196:199], v[200:203], v[34:49]
	global_load_dwordx4 v[70:73], v0, s[22:23] offset:256
	s_waitcnt lgkmcnt(0)
	v_mfma_f32_32x32x16_bf16 v[50:65], v[196:199], v[208:211], v[50:65]
	global_load_dwordx4 v[74:77], v0, s[18:19] offset:256
	ds_read_b128 v[196:199], v171
	ds_read_b128 v[200:203], v171 offset:4096
	ds_read_b128 v[212:215], v172 offset:16384
	ds_read_b128 v[226:229], v172 offset:20480
	v_mfma_f32_32x32x16_bf16 v[18:33], v[204:207], v[208:211], v[18:33]
	global_load_dwordx4 v[78:81], v0, s[24:25] offset:256
	s_waitcnt lgkmcnt(1)
	v_mfma_f32_32x32x16_bf16 v[34:49], v[196:199], v[212:215], v[34:49]
	global_load_dwordx4 v[82:85], v0, s[16:17] offset:256
	v_add_u32_e32 v173, v164, v167
	v_add_u32_e32 v190, v165, v167
	s_waitcnt lgkmcnt(0)
	v_mfma_f32_32x32x16_bf16 v[50:65], v[196:199], v[226:229], v[50:65]
	global_load_dwordx4 v[86:89], v0, s[6:7] offset:256
	ds_read_b128 v[196:199], v173
	ds_read_b128 v[204:207], v173 offset:4096
	v_mfma_f32_32x32x16_bf16 v[2:17], v[200:203], v[212:215], v[2:17]
	global_load_dwordx4 v[90:93], v0, s[0:1] offset:256
	ds_read_b128 v[208:211], v190 offset:16384
	ds_read_b128 v[212:215], v190 offset:20480
	v_mfma_f32_32x32x16_bf16 v[18:33], v[200:203], v[226:229], v[18:33]
	global_load_dwordx4 v[94:97], v0, s[12:13] offset:256
	s_waitcnt lgkmcnt(1)
	v_mfma_f32_32x32x16_bf16 v[34:49], v[196:199], v[208:211], v[34:49]
	s_waitcnt vmcnt(8)
	ds_write_b128 v141, v[98:101] offset:32768
	v_add_u32_e32 v194, v164, v168
	s_waitcnt lgkmcnt(1)
	v_mfma_f32_32x32x16_bf16 v[50:65], v[196:199], v[212:215], v[50:65]
	ds_write_b128 v141, v[102:105] offset:36864
	v_add_u32_e32 v196, v165, v168
	v_mfma_f32_32x32x16_bf16 v[2:17], v[204:207], v[208:211], v[2:17]
	ds_write_b128 v141, v[110:113] offset:40960
	ds_read_b128 v[198:201], v194
	ds_read_b128 v[208:211], v194 offset:4096
	ds_read_b128 v[226:229], v196 offset:16384
	ds_read_b128 v[230:233], v196 offset:20480
	v_mfma_f32_32x32x16_bf16 v[18:33], v[204:207], v[212:215], v[18:33]
	ds_write_b128 v141, v[106:109] offset:45056
	s_waitcnt lgkmcnt(2)
	v_mfma_f32_32x32x16_bf16 v[34:49], v[198:201], v[226:229], v[34:49]
	ds_write_b128 v141, v[114:117] offset:49152
	s_waitcnt lgkmcnt(2)
	v_mfma_f32_32x32x16_bf16 v[50:65], v[198:201], v[230:233], v[50:65]
	ds_write_b128 v141, v[122:125] offset:53248
	v_mfma_f32_32x32x16_bf16 v[2:17], v[208:211], v[226:229], v[2:17]
	ds_write_b128 v141, v[118:121] offset:57344
	v_mfma_f32_32x32x16_bf16 v[18:33], v[208:211], v[230:233], v[18:33]
	ds_write_b128 v141, v[126:129] offset:61440
	s_branch .Lggb_mid
.Lggb_last:
	v_add_u32_e32 v169, v164, v143
	ds_read_b128 v[196:199], v169
	v_add_u32_e32 v170, v165, v143
	ds_read_b128 v[200:203], v170 offset:16384
	ds_read_b128 v[204:207], v169 offset:4096
	ds_read_b128 v[208:211], v170 offset:20480
	v_add_u32_e32 v171, v164, v166
	s_waitcnt lgkmcnt(1)
	v_mfma_f32_32x32x16_bf16 v[2:17], v[204:207], v[200:203], v[2:17]
	v_add_u32_e32 v172, v165, v166
	v_mfma_f32_32x32x16_bf16 v[34:49], v[196:199], v[200:203], v[34:49]
	s_waitcnt lgkmcnt(0)
	v_mfma_f32_32x32x16_bf16 v[50:65], v[196:199], v[208:211], v[50:65]
	ds_read_b128 v[196:199], v171
	ds_read_b128 v[200:203], v171 offset:4096
	ds_read_b128 v[212:215], v172 offset:16384
	ds_read_b128 v[226:229], v172 offset:20480
	v_mfma_f32_32x32x16_bf16 v[18:33], v[204:207], v[208:211], v[18:33]
	s_waitcnt lgkmcnt(1)
	v_mfma_f32_32x32x16_bf16 v[34:49], v[196:199], v[212:215], v[34:49]
	v_add_u32_e32 v173, v164, v167
	v_add_u32_e32 v190, v165, v167
	s_waitcnt lgkmcnt(0)
	v_mfma_f32_32x32x16_bf16 v[50:65], v[196:199], v[226:229], v[50:65]
	ds_read_b128 v[196:199], v173
	ds_read_b128 v[204:207], v173 offset:4096
	v_mfma_f32_32x32x16_bf16 v[2:17], v[200:203], v[212:215], v[2:17]
	ds_read_b128 v[208:211], v190 offset:16384
	ds_read_b128 v[212:215], v190 offset:20480
	v_mfma_f32_32x32x16_bf16 v[18:33], v[200:203], v[226:229], v[18:33]
	s_waitcnt lgkmcnt(1)
	v_mfma_f32_32x32x16_bf16 v[34:49], v[196:199], v[208:211], v[34:49]
	s_waitcnt vmcnt(0)
	ds_write_b128 v141, v[98:101] offset:32768
	v_add_u32_e32 v194, v164, v168
	s_waitcnt lgkmcnt(1)
	v_mfma_f32_32x32x16_bf16 v[50:65], v[196:199], v[212:215], v[50:65]
	ds_write_b128 v141, v[102:105] offset:36864
	v_add_u32_e32 v196, v165, v168
	v_mfma_f32_32x32x16_bf16 v[2:17], v[204:207], v[208:211], v[2:17]
	ds_write_b128 v141, v[110:113] offset:40960
	ds_read_b128 v[198:201], v194
	ds_read_b128 v[208:211], v194 offset:4096
	ds_read_b128 v[226:229], v196 offset:16384
	ds_read_b128 v[230:233], v196 offset:20480
	v_mfma_f32_32x32x16_bf16 v[18:33], v[204:207], v[212:215], v[18:33]
	ds_write_b128 v141, v[106:109] offset:45056
	s_waitcnt lgkmcnt(2)
	v_mfma_f32_32x32x16_bf16 v[34:49], v[198:201], v[226:229], v[34:49]
	ds_write_b128 v141, v[114:117] offset:49152
	s_waitcnt lgkmcnt(2)
	v_mfma_f32_32x32x16_bf16 v[50:65], v[198:201], v[230:233], v[50:65]
	ds_write_b128 v141, v[122:125] offset:53248
	v_mfma_f32_32x32x16_bf16 v[2:17], v[208:211], v[226:229], v[2:17]
	ds_write_b128 v141, v[118:121] offset:57344
	v_mfma_f32_32x32x16_bf16 v[18:33], v[208:211], v[230:233], v[18:33]
	ds_write_b128 v141, v[126:129] offset:61440
; #define GL(...) GLOAD(__VA_ARGS__)
; #define SS(...) SSTORE(__VA_ARGS__)
; template <bool TRANS>
; DI void gemm_kloop(const u16* __restrict__ A, int lda, const u16* __restrict__ W, int ldw, int K, f32x16 (&acc)[2][2], char* lds) {
;     ...
;   for (int kt = 0; kt < KT; kt += 2) {
;     const bool m2 = kt + 2 < KT;
;     if (m2) { GL(SET0, (kt + 2) * 64); }
;     COMPUTE(0);
;     SS(SET1, 1);
;     __syncthreads();
;     if (m2) { GL(SET1, (kt + 3) * 64); }
;     COMPUTE(1);
;     if (m2) { SS(SET0, 0); }
;     __syncthreads();
;   }
.Lggb_mid:
	v_cndmask_b32_e64 v197, 0, 1, s[36:37]
	v_cmp_ne_u32_e64 s[40:41], 1, v197
	s_andn2_b64 vcc, exec, s[36:37]
	s_waitcnt lgkmcnt(0)
	s_barrier
	s_cbranch_vccnz .Lggb_nol1
	ds_read_b128 v[144:147], v169 offset:32768
	ds_read_b128 v[148:151], v170 offset:49152
	ds_read_b128 v[152:155], v169 offset:36864
	ds_read_b128 v[156:159], v170 offset:53248
	s_waitcnt lgkmcnt(2)
	v_mfma_f32_32x32x16_bf16 v[34:49], v[144:147], v[148:151], v[34:49]
	global_load_dwordx4 v[98:101], v0, s[28:29] offset:384
	s_waitcnt lgkmcnt(0)
	v_mfma_f32_32x32x16_bf16 v[50:65], v[144:147], v[156:159], v[50:65]
	global_load_dwordx4 v[102:105], v0, s[22:23] offset:384
	v_mfma_f32_32x32x16_bf16 v[2:17], v[152:155], v[148:151], v[2:17]
	global_load_dwordx4 v[110:113], v0, s[18:19] offset:384
	ds_read_b128 v[144:147], v171 offset:32768
	ds_read_b128 v[148:151], v171 offset:36864
	ds_read_b128 v[198:201], v172 offset:49152
	ds_read_b128 v[202:205], v172 offset:53248
	v_mfma_f32_32x32x16_bf16 v[18:33], v[152:155], v[156:159], v[18:33]
	global_load_dwordx4 v[106:109], v0, s[24:25] offset:384
	s_waitcnt lgkmcnt(1)
	v_mfma_f32_32x32x16_bf16 v[34:49], v[144:147], v[198:201], v[34:49]
	global_load_dwordx4 v[114:117], v0, s[16:17] offset:384
	s_waitcnt lgkmcnt(0)
	v_mfma_f32_32x32x16_bf16 v[50:65], v[144:147], v[202:205], v[50:65]
	global_load_dwordx4 v[122:125], v0, s[6:7] offset:384
	ds_read_b128 v[144:147], v173 offset:32768
	ds_read_b128 v[152:155], v173 offset:36864
	ds_read_b128 v[156:159], v190 offset:49152
	ds_read_b128 v[170:173], v190 offset:53248
	v_mfma_f32_32x32x16_bf16 v[2:17], v[148:151], v[198:201], v[2:17]
	global_load_dwordx4 v[118:121], v0, s[0:1] offset:384
	v_mfma_f32_32x32x16_bf16 v[18:33], v[148:151], v[202:205], v[18:33]
	global_load_dwordx4 v[126:129], v0, s[12:13] offset:384
	s_waitcnt lgkmcnt(1)
	v_mfma_f32_32x32x16_bf16 v[34:49], v[144:147], v[156:159], v[34:49]
	s_waitcnt vmcnt(8)
	ds_write_b128 v141, v[66:69]
	s_waitcnt lgkmcnt(1)
	v_mfma_f32_32x32x16_bf16 v[50:65], v[144:147], v[170:173], v[50:65]
	ds_write_b128 v141, v[70:73] offset:4096
	v_mfma_f32_32x32x16_bf16 v[2:17], v[152:155], v[156:159], v[2:17]
	ds_write_b128 v141, v[74:77] offset:8192
	ds_read_b128 v[144:147], v194 offset:32768
	ds_read_b128 v[148:151], v194 offset:36864
	ds_read_b128 v[156:159], v196 offset:49152
	ds_read_b128 v[196:199], v196 offset:53248
	v_mfma_f32_32x32x16_bf16 v[18:33], v[152:155], v[170:173], v[18:33]
	ds_write_b128 v141, v[78:81] offset:12288
	s_waitcnt lgkmcnt(2)
	v_mfma_f32_32x32x16_bf16 v[34:49], v[144:147], v[156:159], v[34:49]
	ds_write_b128 v141, v[82:85] offset:16384
	s_waitcnt lgkmcnt(2)
	v_mfma_f32_32x32x16_bf16 v[50:65], v[144:147], v[196:199], v[50:65]
	ds_write_b128 v141, v[86:89] offset:20480
	v_mfma_f32_32x32x16_bf16 v[2:17], v[148:151], v[156:159], v[2:17]
	ds_write_b128 v141, v[90:93] offset:24576
	v_mfma_f32_32x32x16_bf16 v[18:33], v[148:151], v[196:199], v[18:33]
	ds_write_b128 v141, v[94:97] offset:28672
	s_branch .LBB0_476
.Lggb_nol1:
	ds_read_b128 v[144:147], v169 offset:32768
	ds_read_b128 v[148:151], v170 offset:49152
	ds_read_b128 v[152:155], v169 offset:36864
	ds_read_b128 v[156:159], v170 offset:53248
	s_waitcnt lgkmcnt(2)
	v_mfma_f32_32x32x16_bf16 v[34:49], v[144:147], v[148:151], v[34:49]
	s_waitcnt lgkmcnt(0)
	v_mfma_f32_32x32x16_bf16 v[50:65], v[144:147], v[156:159], v[50:65]
	v_mfma_f32_32x32x16_bf16 v[2:17], v[152:155], v[148:151], v[2:17]
	ds_read_b128 v[144:147], v171 offset:32768
	ds_read_b128 v[148:151], v171 offset:36864
	ds_read_b128 v[198:201], v172 offset:49152
	ds_read_b128 v[202:205], v172 offset:53248
	v_mfma_f32_32x32x16_bf16 v[18:33], v[152:155], v[156:159], v[18:33]
	s_waitcnt lgkmcnt(1)
	v_mfma_f32_32x32x16_bf16 v[34:49], v[144:147], v[198:201], v[34:49]
	s_waitcnt lgkmcnt(0)
	v_mfma_f32_32x32x16_bf16 v[50:65], v[144:147], v[202:205], v[50:65]
	ds_read_b128 v[144:147], v173 offset:32768
	ds_read_b128 v[152:155], v173 offset:36864
	ds_read_b128 v[156:159], v190 offset:49152
	ds_read_b128 v[170:173], v190 offset:53248
	v_mfma_f32_32x32x16_bf16 v[2:17], v[148:151], v[198:201], v[2:17]
	v_mfma_f32_32x32x16_bf16 v[18:33], v[148:151], v[202:205], v[18:33]
	s_waitcnt lgkmcnt(1)
	v_mfma_f32_32x32x16_bf16 v[34:49], v[144:147], v[156:159], v[34:49]
	s_waitcnt lgkmcnt(0)
	v_mfma_f32_32x32x16_bf16 v[50:65], v[144:147], v[170:173], v[50:65]
	v_mfma_f32_32x32x16_bf16 v[2:17], v[152:155], v[156:159], v[2:17]
	ds_read_b128 v[144:147], v194 offset:32768
	ds_read_b128 v[148:151], v194 offset:36864
	ds_read_b128 v[156:159], v196 offset:49152
	ds_read_b128 v[196:199], v196 offset:53248
	v_mfma_f32_32x32x16_bf16 v[18:33], v[152:155], v[170:173], v[18:33]
	s_waitcnt lgkmcnt(1)
	v_mfma_f32_32x32x16_bf16 v[34:49], v[144:147], v[156:159], v[34:49]
	s_waitcnt lgkmcnt(0)
	v_mfma_f32_32x32x16_bf16 v[50:65], v[144:147], v[196:199], v[50:65]
	v_mfma_f32_32x32x16_bf16 v[2:17], v[148:151], v[156:159], v[2:17]
	v_mfma_f32_32x32x16_bf16 v[18:33], v[148:151], v[196:199], v[18:33]
	s_branch .LBB0_476
